# attention loop body rewritten: two score accumulators, QK MFMAs interleaved into softmax VALU, first 16 PV MFMAs interleaved into last softmax block (on top of stagger)
# speedup vs baseline: 1.0078x; 1.0078x over previous
; #define LAS __attribute__((address_space(3)))
; #define ATT_VTR(p) __builtin_bit_cast(s16x4, __builtin_amdgcn_ds_read_tr16_b64_v4i16((LAS s16x4*)(p)))
; DI void attn_unit(LAS unsigned char* lds, const bf16_t* P, bf16_t* Am, int qrow0, int h, int ntiles, int krow_ctx, int krow_lat,
;                   float lam, const float* subw, float outscale) {
;     ...
;     int s0 = 0, s1 = 1, s2 = 2;
;     for (int t = 0; t < ntiles; ++t) {
;         const bool more = (t + 2 < ntiles);
;         if (more) ATT_DMA_KV(t + 2, s2);
;         LAS unsigned char* kp = lds + s0 * 16384 + kb_off;
;         LAS unsigned char* vp0 = lds + s0 * 16384 + vb_par[0];
;         LAS unsigned char* vp1 = lds + s0 * 16384 + vb_par[1];
;         u32x4 pwa[4], pwb[4];
;     ...
;         ATT_QKP(ATT_QA, lsa, pwa);
;         ATT_QKP(ATT_QB, lsb, pwb);
;     ...
;         {
;             s16x4 vl[2][2], vh[2][2];
; #pragma unroll
;             for (int i = 0; i < 2; ++i) { LAS unsigned char* vq = (i ? vp1 : vp0); vl[0][i] = ATT_VTR(vq); vh[0][i] = ATT_VTR(vq + 1024); }
; #pragma unroll
;             for (int gi = 0; gi < 8; ++gi) { const int ks = gi >> 1, dp = gi & 1;
;                 if (gi < 7) { const int ks2 = (gi + 1) >> 1, dp2 = (gi + 1) & 1;
; #pragma unroll
;                     for (int i = 0; i < 2; ++i) { LAS unsigned char* vq = (i ? vp1 : vp0) + dp2 * 8192 + ks2 * 2048; vl[(gi + 1) & 1][i] = ATT_VTR(vq); vh[(gi + 1) & 1][i] = ATT_VTR(vq + 1024); } }
;                 __builtin_amdgcn_sched_barrier(0x406);
; #pragma unroll
;                 for (int i = 0; i < 2; ++i) { const int d0 = 2 * dp + i; const s16x4 lo = vl[gi & 1][i], hh = vh[gi & 1][i];
;                     const bf16x8 vf = {lo[0], lo[1], lo[2], lo[3], hh[0], hh[1], hh[2], hh[3]};
;                     oa[d0] = __builtin_amdgcn_mfma_f32_32x32x16_bf16(vf, __builtin_bit_cast(bf16x8, pwa[ks]), oa[d0], 0, 0, 0);
;                     ob[d0] = __builtin_amdgcn_mfma_f32_32x32x16_bf16(vf, __builtin_bit_cast(bf16x8, pwb[ks]), ob[d0], 0, 0, 0); }
;                 __builtin_amdgcn_sched_barrier(0x406);
;             }
.LBB0_333:
	s_lshl_b32 s0, s5, 14
	s_add_i32 s6, s0, s63
	v_add_u32_e32 v236, s6, v244
	v_add_u32_e32 v232, v236, v222
	ds_read_b128 v[176:179], v232
	v_add_u32_e32 v233, v236, v241
	ds_read_b128 v[180:183], v233
	v_add_u32_e32 v234, v236, v240
	ds_read_b128 v[184:187], v234
	v_add_u32_e32 v235, v236, v248
	ds_read_b128 v[188:191], v235
	ds_read_b128 v[224:227], v253
	ds_read_b128 v[228:231], v253 offset:1024
	ds_read_b128 v[168:171], v253 offset:2048
	ds_read_b128 v[160:163], v253 offset:3072
	v_add_u32_e32 v218, s0, v249
	v_add_u32_e32 v243, s0, v245
	s_add_i32 s4, s4, 1
	s_add_i32 s58, s58, 64
	s_waitcnt lgkmcnt(7)
	v_mfma_f32_32x32x16_bf16 v[128:143], v[176:179], v[144:147], 0
	s_waitcnt lgkmcnt(6)
	v_mfma_f32_32x32x16_bf16 v[128:143], v[180:183], v[148:151], v[128:143]
	s_waitcnt lgkmcnt(5)
	v_mfma_f32_32x32x16_bf16 v[128:143], v[184:187], v[152:155], v[128:143]
	s_waitcnt lgkmcnt(4)
	v_mfma_f32_32x32x16_bf16 v[128:143], v[188:191], v[156:159], v[128:143]
	s_waitcnt lgkmcnt(3)
	v_mfma_f32_32x32x16_bf16 v[192:207], v[176:179], v[224:227], 0
	s_waitcnt lgkmcnt(2)
	v_mfma_f32_32x32x16_bf16 v[192:207], v[180:183], v[228:231], v[192:207]
	s_waitcnt lgkmcnt(1)
	v_mfma_f32_32x32x16_bf16 v[192:207], v[184:187], v[168:171], v[192:207]
	s_waitcnt lgkmcnt(0)
	v_mfma_f32_32x32x16_bf16 v[192:207], v[188:191], v[160:163], v[192:207]
	ds_read_b128 v[176:179], v232 offset:4096
	ds_read_b128 v[180:183], v233 offset:4096
	ds_read_b128 v[184:187], v234 offset:4096
	ds_read_b128 v[188:191], v235 offset:4096
	v_exp_f32_e32 v128, v128
	v_exp_f32_e32 v129, v129
	v_exp_f32_e32 v130, v130
	v_exp_f32_e32 v131, v131
	v_add_f32_e32 v164, v128, v130
	v_add_f32_e32 v165, v129, v131
	v_exp_f32_e32 v132, v132
	v_exp_f32_e32 v133, v133
	v_add_f32_e32 v164, v164, v132
	v_add_f32_e32 v165, v165, v133
	v_exp_f32_e32 v134, v134
	v_exp_f32_e32 v135, v135
	v_add_f32_e32 v164, v164, v134
	v_add_f32_e32 v165, v165, v135
	v_exp_f32_e32 v136, v136
	v_exp_f32_e32 v137, v137
	v_add_f32_e32 v164, v164, v136
	v_add_f32_e32 v165, v165, v137
	v_exp_f32_e32 v138, v138
	v_exp_f32_e32 v139, v139
	v_add_f32_e32 v164, v164, v138
	v_add_f32_e32 v165, v165, v139
	v_exp_f32_e32 v140, v140
	v_exp_f32_e32 v141, v141
	v_add_f32_e32 v164, v164, v140
	v_add_f32_e32 v165, v165, v141
	v_exp_f32_e32 v142, v142
	v_exp_f32_e32 v143, v143
	v_add_f32_e32 v210, v164, v142
	v_add_f32_e32 v212, v165, v143
	v_cvt_pk_bf16_f32 v172, v128, v129
	v_cvt_pk_bf16_f32 v173, v130, v131
	v_cvt_pk_bf16_f32 v174, v132, v133
	v_cvt_pk_bf16_f32 v175, v134, v135
	v_cvt_pk_bf16_f32 v164, v136, v137
	v_cvt_pk_bf16_f32 v165, v138, v139
	v_cvt_pk_bf16_f32 v166, v140, v141
	v_cvt_pk_bf16_f32 v167, v142, v143
	s_waitcnt lgkmcnt(3)
	v_mfma_f32_32x32x16_bf16 v[128:143], v[176:179], v[144:147], 0
	v_exp_f32_e32 v192, v192
	v_exp_f32_e32 v193, v193
	v_exp_f32_e32 v194, v194
	v_exp_f32_e32 v195, v195
	v_add_f32_e32 v236, v192, v194
	v_add_f32_e32 v237, v193, v195
	s_waitcnt lgkmcnt(2)
	v_mfma_f32_32x32x16_bf16 v[128:143], v[180:183], v[148:151], v[128:143]
	v_exp_f32_e32 v196, v196
	v_exp_f32_e32 v197, v197
	v_add_f32_e32 v236, v236, v196
	v_add_f32_e32 v237, v237, v197
	v_exp_f32_e32 v198, v198
	v_exp_f32_e32 v199, v199
	s_waitcnt lgkmcnt(1)
	v_mfma_f32_32x32x16_bf16 v[128:143], v[184:187], v[152:155], v[128:143]
	v_add_f32_e32 v236, v236, v198
	v_add_f32_e32 v237, v237, v199
	v_exp_f32_e32 v200, v200
	v_exp_f32_e32 v201, v201
	v_add_f32_e32 v236, v236, v200
	v_add_f32_e32 v237, v237, v201
	s_waitcnt lgkmcnt(0)
	v_mfma_f32_32x32x16_bf16 v[128:143], v[188:191], v[156:159], v[128:143]
	v_exp_f32_e32 v202, v202
	v_exp_f32_e32 v203, v203
	v_add_f32_e32 v236, v236, v202
	v_add_f32_e32 v237, v237, v203
	v_exp_f32_e32 v204, v204
	v_exp_f32_e32 v205, v205
	v_add_f32_e32 v236, v236, v204
	v_add_f32_e32 v237, v237, v205
	v_exp_f32_e32 v206, v206
	v_exp_f32_e32 v207, v207
	v_add_f32_e32 v211, v236, v206
	v_add_f32_e32 v213, v237, v207
	v_cvt_pk_bf16_f32 v232, v192, v193
	v_cvt_pk_bf16_f32 v233, v194, v195
	v_cvt_pk_bf16_f32 v234, v196, v197
	v_cvt_pk_bf16_f32 v235, v198, v199
	v_cvt_pk_bf16_f32 v236, v200, v201
	v_cvt_pk_bf16_f32 v237, v202, v203
	v_cvt_pk_bf16_f32 v238, v204, v205
	v_cvt_pk_bf16_f32 v239, v206, v207
	v_mfma_f32_32x32x16_bf16 v[192:207], v[176:179], v[224:227], 0
	v_exp_f32_e32 v128, v128
	v_exp_f32_e32 v129, v129
	v_exp_f32_e32 v130, v130
	v_exp_f32_e32 v131, v131
	v_add_f32_e32 v224, v128, v130
	v_add_f32_e32 v225, v129, v131
	v_mfma_f32_32x32x16_bf16 v[192:207], v[180:183], v[228:231], v[192:207]
	v_exp_f32_e32 v132, v132
	v_exp_f32_e32 v133, v133
	v_add_f32_e32 v224, v224, v132
	v_add_f32_e32 v225, v225, v133
	v_exp_f32_e32 v134, v134
	v_exp_f32_e32 v135, v135
	v_mfma_f32_32x32x16_bf16 v[192:207], v[184:187], v[168:171], v[192:207]
	v_add_f32_e32 v224, v224, v134
	v_add_f32_e32 v225, v225, v135
	v_exp_f32_e32 v136, v136
	v_exp_f32_e32 v137, v137
	v_add_f32_e32 v224, v224, v136
	v_add_f32_e32 v225, v225, v137
	v_mfma_f32_32x32x16_bf16 v[192:207], v[188:191], v[160:163], v[192:207]
	v_exp_f32_e32 v138, v138
	v_exp_f32_e32 v139, v139
	v_add_f32_e32 v224, v224, v138
	v_add_f32_e32 v225, v225, v139
	ds_read_b64_tr_b16 v[176:177], v218 offset:49152
	ds_read_b64_tr_b16 v[178:179], v218 offset:50176
	ds_read_b64_tr_b16 v[180:181], v243 offset:49152
	ds_read_b64_tr_b16 v[182:183], v243 offset:50176
	v_exp_f32_e32 v140, v140
	v_exp_f32_e32 v141, v141
	v_add_f32_e32 v224, v224, v140
	v_add_f32_e32 v225, v225, v141
	ds_read_b64_tr_b16 v[184:185], v218 offset:57344
	ds_read_b64_tr_b16 v[186:187], v218 offset:58368
	ds_read_b64_tr_b16 v[188:189], v243 offset:57344
	ds_read_b64_tr_b16 v[190:191], v243 offset:58368
	v_exp_f32_e32 v142, v142
	v_exp_f32_e32 v143, v143
	v_add_f32_e32 v214, v224, v142
	v_add_f32_e32 v216, v225, v143
	v_cvt_pk_bf16_f32 v168, v128, v129
	v_cvt_pk_bf16_f32 v169, v130, v131
	v_cvt_pk_bf16_f32 v170, v132, v133
	v_cvt_pk_bf16_f32 v171, v134, v135
	v_cvt_pk_bf16_f32 v160, v136, v137
	v_cvt_pk_bf16_f32 v161, v138, v139
	v_cvt_pk_bf16_f32 v162, v140, v141
	v_cvt_pk_bf16_f32 v163, v142, v143
	s_cmp_eq_u32 s38, 0
	s_cbranch_scc1 .Latt_midskip_l
	s_waitcnt vmcnt(0) lgkmcnt(0)
	s_barrier
	s_cmp_gt_u32 s4, s1
	s_cbranch_scc1 .Latt_midskip_l
	s_add_i32 s6, s58, 0xffffffc0
	s_mul_hi_i32 s7, s6, 0x3000
	s_mul_i32 s6, s6, 0x3000
	s_add_u32 s6, s50, s6
	s_addc_u32 s7, s51, s7
	s_add_u32 s8, s6, 0x80
	s_addc_u32 s9, s7, 0
	s_lshl_b32 s10, s60, 14
	s_mov_b32 s11, m0
	s_add_i32 s10, s10, s61
	s_mov_b32 m0, s10
	s_nop 0
	global_load_lds_dwordx4 v251, s[6:7]
	s_addk_i32 s10, 0x2000
	s_mov_b32 m0, s10
	s_nop 0
	global_load_lds_dwordx4 v251, s[8:9]
	s_add_i32 s10, s10, 0xa000
	s_mov_b32 m0, s10
	s_nop 0
	global_load_lds_dwordx4 v252, s[6:7]
	s_addk_i32 s10, 0x2000
	s_mov_b32 m0, s10
	s_nop 0
	global_load_lds_dwordx4 v252, s[8:9]
	s_mov_b32 m0, s11
; #define LAS __attribute__((address_space(3)))
; #define ATT_VTR(p) __builtin_bit_cast(s16x4, __builtin_amdgcn_ds_read_tr16_b64_v4i16((LAS s16x4*)(p)))
; DI void attn_unit(LAS unsigned char* lds, const bf16_t* P, bf16_t* Am, int qrow0, int h, int ntiles, int krow_ctx, int krow_lat,
;                   float lam, const float* subw, float outscale) {
;     ...
;         {
;             s16x4 vl[2][2], vh[2][2];
; #pragma unroll
;             for (int i = 0; i < 2; ++i) { LAS unsigned char* vq = (i ? vp1 : vp0); vl[0][i] = ATT_VTR(vq); vh[0][i] = ATT_VTR(vq + 1024); }
; #pragma unroll
;             for (int gi = 0; gi < 8; ++gi) { const int ks = gi >> 1, dp = gi & 1;
;                 if (gi < 7) { const int ks2 = (gi + 1) >> 1, dp2 = (gi + 1) & 1;
; #pragma unroll
;                     for (int i = 0; i < 2; ++i) { LAS unsigned char* vq = (i ? vp1 : vp0) + dp2 * 8192 + ks2 * 2048; vl[(gi + 1) & 1][i] = ATT_VTR(vq); vh[(gi + 1) & 1][i] = ATT_VTR(vq + 1024); } }
;                 __builtin_amdgcn_sched_barrier(0x406);
; #pragma unroll
;                 for (int i = 0; i < 2; ++i) { const int d0 = 2 * dp + i; const s16x4 lo = vl[gi & 1][i], hh = vh[gi & 1][i];
;                     const bf16x8 vf = {lo[0], lo[1], lo[2], lo[3], hh[0], hh[1], hh[2], hh[3]};
;                     oa[d0] = __builtin_amdgcn_mfma_f32_32x32x16_bf16(vf, __builtin_bit_cast(bf16x8, pwa[ks]), oa[d0], 0, 0, 0);
;                     ob[d0] = __builtin_amdgcn_mfma_f32_32x32x16_bf16(vf, __builtin_bit_cast(bf16x8, pwb[ks]), ob[d0], 0, 0, 0); }
;                 __builtin_amdgcn_sched_barrier(0x406);
;             }
.Latt_midskip_l:
	v_exp_f32_e32 v192, v192
	s_waitcnt lgkmcnt(6)
	v_mfma_f32_32x32x16_bf16 v[112:127], v[176:179], v[172:175], v[112:127]
	v_exp_f32_e32 v193, v193
	v_exp_f32_e32 v194, v194
	v_mfma_f32_32x32x16_bf16 v[48:63], v[176:179], v[232:235], v[48:63]
	v_exp_f32_e32 v195, v195
	v_add_f32_e32 v128, v192, v194
	s_waitcnt lgkmcnt(4)
	v_mfma_f32_32x32x16_bf16 v[96:111], v[180:183], v[172:175], v[96:111]
	v_add_f32_e32 v129, v193, v195
	v_exp_f32_e32 v196, v196
	v_mfma_f32_32x32x16_bf16 v[32:47], v[180:183], v[232:235], v[32:47]
	v_exp_f32_e32 v197, v197
	ds_read_b64_tr_b16 v[176:177], v218 offset:51200
	ds_read_b64_tr_b16 v[178:179], v218 offset:52224
	ds_read_b64_tr_b16 v[180:181], v243 offset:51200
	ds_read_b64_tr_b16 v[182:183], v243 offset:52224
	v_add_f32_e32 v128, v128, v196
	v_add_f32_e32 v129, v129, v197
	s_waitcnt lgkmcnt(6)
	v_mfma_f32_32x32x16_bf16 v[80:95], v[184:187], v[172:175], v[80:95]
	v_exp_f32_e32 v198, v198
	v_exp_f32_e32 v199, v199
	v_mfma_f32_32x32x16_bf16 v[16:31], v[184:187], v[232:235], v[16:31]
	v_add_f32_e32 v128, v128, v198
	v_add_f32_e32 v129, v129, v199
	s_waitcnt lgkmcnt(4)
	v_mfma_f32_32x32x16_bf16 v[64:79], v[188:191], v[172:175], v[64:79]
	v_exp_f32_e32 v200, v200
	v_exp_f32_e32 v201, v201
	v_mfma_f32_32x32x16_bf16 v[0:15], v[188:191], v[232:235], v[0:15]
	v_add_f32_e32 v128, v128, v200
	ds_read_b64_tr_b16 v[184:185], v218 offset:59392
	ds_read_b64_tr_b16 v[186:187], v218 offset:60416
	ds_read_b64_tr_b16 v[188:189], v243 offset:59392
	ds_read_b64_tr_b16 v[190:191], v243 offset:60416
	v_add_f32_e32 v129, v129, v201
	v_exp_f32_e32 v202, v202
	s_waitcnt lgkmcnt(6)
	v_mfma_f32_32x32x16_bf16 v[112:127], v[176:179], v[164:167], v[112:127]
	v_exp_f32_e32 v203, v203
	v_add_f32_e32 v128, v128, v202
	v_mfma_f32_32x32x16_bf16 v[48:63], v[176:179], v[236:239], v[48:63]
	v_add_f32_e32 v129, v129, v203
	v_exp_f32_e32 v204, v204
	s_waitcnt lgkmcnt(4)
	v_mfma_f32_32x32x16_bf16 v[96:111], v[180:183], v[164:167], v[96:111]
	v_exp_f32_e32 v205, v205
	v_add_f32_e32 v128, v128, v204
	v_mfma_f32_32x32x16_bf16 v[32:47], v[180:183], v[236:239], v[32:47]
	v_add_f32_e32 v129, v129, v205
	ds_read_b64_tr_b16 v[176:177], v218 offset:53248
	ds_read_b64_tr_b16 v[178:179], v218 offset:54272
	ds_read_b64_tr_b16 v[180:181], v243 offset:53248
	ds_read_b64_tr_b16 v[182:183], v243 offset:54272
	v_exp_f32_e32 v206, v206
	v_exp_f32_e32 v207, v207
	s_waitcnt lgkmcnt(6)
	v_mfma_f32_32x32x16_bf16 v[80:95], v[184:187], v[164:167], v[80:95]
	v_add_f32_e32 v215, v128, v206
	v_add_f32_e32 v217, v129, v207
	v_mfma_f32_32x32x16_bf16 v[16:31], v[184:187], v[236:239], v[16:31]
	v_cvt_pk_bf16_f32 v132, v192, v193
	v_cvt_pk_bf16_f32 v133, v194, v195
	s_waitcnt lgkmcnt(4)
	v_mfma_f32_32x32x16_bf16 v[64:79], v[188:191], v[164:167], v[64:79]
	v_cvt_pk_bf16_f32 v134, v196, v197
	v_cvt_pk_bf16_f32 v135, v198, v199
	v_mfma_f32_32x32x16_bf16 v[0:15], v[188:191], v[236:239], v[0:15]
	v_cvt_pk_bf16_f32 v128, v200, v201
	ds_read_b64_tr_b16 v[184:185], v218 offset:61440
	ds_read_b64_tr_b16 v[186:187], v218 offset:62464
	ds_read_b64_tr_b16 v[188:189], v243 offset:61440
	ds_read_b64_tr_b16 v[190:191], v243 offset:62464
	v_cvt_pk_bf16_f32 v129, v202, v203
	v_cvt_pk_bf16_f32 v130, v204, v205
	v_cvt_pk_bf16_f32 v131, v206, v207
	v_pk_add_f32 v[224:225], v[210:211], v[212:213]
	v_pk_add_f32 v[224:225], v[208:209], v[224:225]
	v_add_f32_e32 v226, v214, v216
	v_add_f32_e32 v227, v215, v217
	v_add_f32_e32 v208, v224, v226
	v_add_f32_e32 v209, v225, v227
	s_waitcnt lgkmcnt(6)
	v_mfma_f32_32x32x16_bf16 v[112:127], v[176:179], v[168:171], v[112:127]
	v_mfma_f32_32x32x16_bf16 v[48:63], v[176:179], v[132:135], v[48:63]
	s_waitcnt lgkmcnt(4)
	v_mfma_f32_32x32x16_bf16 v[96:111], v[180:183], v[168:171], v[96:111]
	v_mfma_f32_32x32x16_bf16 v[32:47], v[180:183], v[132:135], v[32:47]
	ds_read_b64_tr_b16 v[176:177], v218 offset:55296
	ds_read_b64_tr_b16 v[178:179], v218 offset:56320
	ds_read_b64_tr_b16 v[180:181], v243 offset:55296
	ds_read_b64_tr_b16 v[182:183], v243 offset:56320
	s_waitcnt lgkmcnt(6)
	v_mfma_f32_32x32x16_bf16 v[80:95], v[184:187], v[168:171], v[80:95]
	v_mfma_f32_32x32x16_bf16 v[16:31], v[184:187], v[132:135], v[16:31]
	s_waitcnt lgkmcnt(4)
	v_mfma_f32_32x32x16_bf16 v[64:79], v[188:191], v[168:171], v[64:79]
	v_mfma_f32_32x32x16_bf16 v[0:15], v[188:191], v[132:135], v[0:15]
	ds_read_b64_tr_b16 v[184:185], v218 offset:63488
	ds_read_b64_tr_b16 v[186:187], v218 offset:64512
	ds_read_b64_tr_b16 v[188:189], v243 offset:63488
	ds_read_b64_tr_b16 v[190:191], v243 offset:64512
	s_waitcnt lgkmcnt(6)
	v_mfma_f32_32x32x16_bf16 v[112:127], v[176:179], v[160:163], v[112:127]
	v_mfma_f32_32x32x16_bf16 v[48:63], v[176:179], v[128:131], v[48:63]
	s_waitcnt lgkmcnt(4)
	v_mfma_f32_32x32x16_bf16 v[96:111], v[180:183], v[160:163], v[96:111]
	v_mfma_f32_32x32x16_bf16 v[32:47], v[180:183], v[128:131], v[32:47]
	s_cmp_lg_u32 s38, 0
	s_cbranch_scc1 .Latt_endskip_l
	s_waitcnt vmcnt(0) lgkmcnt(0)
	s_barrier
; #define LAS __attribute__((address_space(3)))
; #define ATT_WAIT_BAR() asm volatile("s_waitcnt vmcnt(0) lgkmcnt(0)\n\ts_barrier" ::: "memory")
; DI void attn_unit(LAS unsigned char* lds, const bf16_t* P, bf16_t* Am, int qrow0, int h, int ntiles, int krow_ctx, int krow_lat,
;                   float lam, const float* subw, float outscale) {
;     ...
;             }
;         }
;         ATT_WAIT_BAR();
;         { const int tmp = s0; s0 = s1; s1 = s2; s2 = tmp; }
;     }
;     ...
;     lsa = sum_x32(lsa); lsb = sum_x32(lsb);
;     const float inva = 1.0f / lsa, invb = 1.0f / lsb;
;     int tid2 = threadIdx.x; asm volatile("" : "+v"(tid2));
;     const int lane2 = tid2 & 63, r32e = lane2 & 31, hie = lane2 >> 5;
;     LAS float* xch = (LAS float*)lds + g * 8192;
;     if (n == 1) { const float sa = inva * lam, sb = invb * lam;
; #pragma unroll
;         for (int d0 = 0; d0 < 4; ++d0)
; #pragma unroll
;             for (int r = 0; r < 16; ++r) { xch[(d0 * 16 + r) * 64 + lane2] = oa[d0][r] * sa; xch[4096 + (d0 * 16 + r) * 64 + lane2] = ob[d0][r] * sb; } }
.Latt_endskip_l:
	s_waitcnt lgkmcnt(2)
	v_mfma_f32_32x32x16_bf16 v[80:95], v[184:187], v[160:163], v[80:95]
	v_mfma_f32_32x32x16_bf16 v[16:31], v[184:187], v[128:131], v[16:31]
	s_waitcnt lgkmcnt(0)
	v_mfma_f32_32x32x16_bf16 v[64:79], v[188:191], v[160:163], v[64:79]
	v_mfma_f32_32x32x16_bf16 v[0:15], v[188:191], v[128:131], v[0:15]
	s_cmp_eq_u32 s59, s4
	s_cbranch_scc0 .LBB0_331
	v_mov_b32_e32 v128, v208
	s_nop 1
	v_permlane32_swap_b32_e32 v208, v128
	v_add_f32_e32 v128, v208, v128
	v_div_scale_f32 v130, s[0:1], v128, v128, 1.0
	v_rcp_f32_e32 v131, v130
	v_mov_b32_e32 v129, v209
	s_nop 1
	v_permlane32_swap_b32_e32 v209, v129
	v_fma_f32 v132, -v130, v131, 1.0
	v_fmac_f32_e32 v131, v132, v131
	v_div_scale_f32 v132, vcc, 1.0, v128, 1.0
	v_mul_f32_e32 v133, v132, v131
	v_fma_f32 v134, -v130, v133, v132
	v_fmac_f32_e32 v133, v134, v131
	v_fma_f32 v130, -v130, v133, v132
	v_add_f32_e32 v129, v209, v129
	v_div_fmas_f32 v130, v130, v131, v133
	v_div_fixup_f32 v138, v130, v128, 1.0
	v_div_scale_f32 v128, s[0:1], v129, v129, 1.0
	v_rcp_f32_e32 v130, v128
	s_lshl_b32 s0, s39, 15
	s_add_i32 s0, s0, 0
	s_cmp_eq_u32 s38, 1
	v_fma_f32 v131, -v128, v130, 1.0
	v_fmac_f32_e32 v130, v131, v130
	v_div_scale_f32 v131, vcc, 1.0, v129, 1.0
	v_mul_f32_e32 v132, v131, v130
	v_fma_f32 v133, -v128, v132, v131
	v_fmac_f32_e32 v132, v133, v130
	v_fma_f32 v128, -v128, v132, v131
	v_div_fmas_f32 v128, v128, v130, v132
	v_div_fixup_f32 v136, v128, v129, 1.0
	v_mov_b32_e32 v128, v220
	s_nop 0
	v_and_b32_e32 v129, 63, v128
	v_lshl_add_u32 v214, v129, 2, s0
	s_cbranch_scc0 .LBB0_336
	s_waitcnt vmcnt(0) lgkmcnt(0)
	s_barrier
	v_mul_f32_e32 v130, s19, v138
	v_mul_f32_e32 v131, s19, v136
	v_mul_f32_e32 v132, v112, v130
	v_mul_f32_e32 v134, v113, v130
	v_mul_f32_e32 v133, v48, v131
	ds_write2st64_b32 v214, v132, v134 offset1:1
	v_mul_f32_e32 v132, v49, v131
	ds_write2st64_b32 v214, v133, v132 offset0:64 offset1:65
	v_mul_f32_e32 v132, v114, v130
	v_mul_f32_e32 v134, v115, v130
	v_mul_f32_e32 v133, v50, v131
	ds_write2st64_b32 v214, v132, v134 offset0:2 offset1:3
	v_mul_f32_e32 v132, v51, v131
	ds_write2st64_b32 v214, v133, v132 offset0:66 offset1:67
	v_mul_f32_e32 v132, v116, v130
	v_mul_f32_e32 v134, v117, v130
	v_mul_f32_e32 v133, v52, v131
	ds_write2st64_b32 v214, v132, v134 offset0:4 offset1:5
	v_mul_f32_e32 v132, v53, v131
	ds_write2st64_b32 v214, v133, v132 offset0:68 offset1:69
	v_mul_f32_e32 v132, v118, v130
	v_mul_f32_e32 v134, v119, v130
	v_mul_f32_e32 v133, v54, v131
	ds_write2st64_b32 v214, v132, v134 offset0:6 offset1:7
	v_mul_f32_e32 v132, v55, v131
	ds_write2st64_b32 v214, v133, v132 offset0:70 offset1:71
	v_mul_f32_e32 v132, v120, v130
	v_mul_f32_e32 v134, v121, v130
	v_mul_f32_e32 v133, v56, v131
	ds_write2st64_b32 v214, v132, v134 offset0:8 offset1:9
	v_mul_f32_e32 v132, v57, v131
	ds_write2st64_b32 v214, v133, v132 offset0:72 offset1:73
	v_mul_f32_e32 v132, v122, v130
	v_mul_f32_e32 v134, v123, v130
	v_mul_f32_e32 v133, v58, v131
	ds_write2st64_b32 v214, v132, v134 offset0:10 offset1:11
	v_mul_f32_e32 v132, v59, v131
	ds_write2st64_b32 v214, v133, v132 offset0:74 offset1:75
	v_mul_f32_e32 v132, v124, v130
	v_mul_f32_e32 v134, v125, v130
	v_mul_f32_e32 v133, v60, v131
	ds_write2st64_b32 v214, v132, v134 offset0:12 offset1:13
	v_mul_f32_e32 v132, v61, v131
	ds_write2st64_b32 v214, v133, v132 offset0:76 offset1:77
	v_mul_f32_e32 v132, v126, v130
	v_mul_f32_e32 v134, v127, v130
	v_mul_f32_e32 v133, v62, v131
	ds_write2st64_b32 v214, v132, v134 offset0:14 offset1:15
	v_mul_f32_e32 v132, v63, v131
	ds_write2st64_b32 v214, v133, v132 offset0:78 offset1:79
	v_mul_f32_e32 v132, v96, v130
	v_mul_f32_e32 v134, v97, v130
	v_mul_f32_e32 v133, v32, v131
	ds_write2st64_b32 v214, v132, v134 offset0:16 offset1:17
	v_mul_f32_e32 v132, v33, v131
	ds_write2st64_b32 v214, v133, v132 offset0:80 offset1:81
	v_mul_f32_e32 v132, v98, v130
	v_mul_f32_e32 v134, v99, v130
	v_mul_f32_e32 v133, v34, v131
	ds_write2st64_b32 v214, v132, v134 offset0:18 offset1:19
	v_mul_f32_e32 v132, v35, v131
	ds_write2st64_b32 v214, v133, v132 offset0:82 offset1:83
	v_mul_f32_e32 v132, v100, v130
	v_mul_f32_e32 v134, v101, v130
	v_mul_f32_e32 v133, v36, v131
	ds_write2st64_b32 v214, v132, v134 offset0:20 offset1:21
	v_mul_f32_e32 v132, v37, v131
	ds_write2st64_b32 v214, v133, v132 offset0:84 offset1:85
	v_mul_f32_e32 v132, v102, v130
	v_mul_f32_e32 v134, v103, v130
	v_mul_f32_e32 v133, v38, v131
	ds_write2st64_b32 v214, v132, v134 offset0:22 offset1:23
	v_mul_f32_e32 v132, v39, v131
	ds_write2st64_b32 v214, v133, v132 offset0:86 offset1:87
	v_mul_f32_e32 v132, v104, v130
	v_mul_f32_e32 v134, v105, v130
	v_mul_f32_e32 v133, v40, v131
	ds_write2st64_b32 v214, v132, v134 offset0:24 offset1:25
; DI void attn_unit(LAS unsigned char* lds, const bf16_t* P, bf16_t* Am, int qrow0, int h, int ntiles, int krow_ctx, int krow_lat,
;                   float lam, const float* subw, float outscale) {
;     ...
;     if (n == 1) { const float sa = inva * lam, sb = invb * lam;
; #pragma unroll
;         for (int d0 = 0; d0 < 4; ++d0)
; #pragma unroll
;             for (int r = 0; r < 16; ++r) { xch[(d0 * 16 + r) * 64 + lane2] = oa[d0][r] * sa; xch[4096 + (d0 * 16 + r) * 64 + lane2] = ob[d0][r] * sb; } }
	v_mul_f32_e32 v132, v41, v131
	ds_write2st64_b32 v214, v133, v132 offset0:88 offset1:89
	v_mul_f32_e32 v132, v106, v130
	v_mul_f32_e32 v134, v107, v130
	v_mul_f32_e32 v133, v42, v131
	ds_write2st64_b32 v214, v132, v134 offset0:26 offset1:27
	v_mul_f32_e32 v132, v43, v131
	ds_write2st64_b32 v214, v133, v132 offset0:90 offset1:91
	v_mul_f32_e32 v132, v108, v130
	v_mul_f32_e32 v134, v109, v130
	v_mul_f32_e32 v133, v44, v131
	ds_write2st64_b32 v214, v132, v134 offset0:28 offset1:29
	v_mul_f32_e32 v132, v45, v131
	ds_write2st64_b32 v214, v133, v132 offset0:92 offset1:93
	v_mul_f32_e32 v132, v110, v130
	v_mul_f32_e32 v134, v111, v130
	v_mul_f32_e32 v133, v46, v131
	ds_write2st64_b32 v214, v132, v134 offset0:30 offset1:31
	v_mul_f32_e32 v132, v47, v131
	ds_write2st64_b32 v214, v133, v132 offset0:94 offset1:95
	v_mul_f32_e32 v132, v80, v130
	v_mul_f32_e32 v134, v81, v130
	v_mul_f32_e32 v133, v16, v131
	ds_write2st64_b32 v214, v132, v134 offset0:32 offset1:33
	v_mul_f32_e32 v132, v17, v131
	ds_write2st64_b32 v214, v133, v132 offset0:96 offset1:97
	v_mul_f32_e32 v132, v82, v130
	v_mul_f32_e32 v134, v83, v130
	v_mul_f32_e32 v133, v18, v131
	ds_write2st64_b32 v214, v132, v134 offset0:34 offset1:35
	v_mul_f32_e32 v132, v19, v131
	ds_write2st64_b32 v214, v133, v132 offset0:98 offset1:99
	v_mul_f32_e32 v132, v84, v130
	v_mul_f32_e32 v134, v85, v130
	v_mul_f32_e32 v133, v20, v131
	ds_write2st64_b32 v214, v132, v134 offset0:36 offset1:37
	v_mul_f32_e32 v132, v21, v131
	ds_write2st64_b32 v214, v133, v132 offset0:100 offset1:101
	v_mul_f32_e32 v132, v86, v130
	v_mul_f32_e32 v134, v87, v130
	v_mul_f32_e32 v133, v22, v131
	ds_write2st64_b32 v214, v132, v134 offset0:38 offset1:39
	v_mul_f32_e32 v132, v23, v131
	ds_write2st64_b32 v214, v133, v132 offset0:102 offset1:103
	v_mul_f32_e32 v132, v88, v130
	v_mul_f32_e32 v134, v89, v130
	v_mul_f32_e32 v133, v24, v131
	ds_write2st64_b32 v214, v132, v134 offset0:40 offset1:41
	v_mul_f32_e32 v132, v25, v131
	ds_write2st64_b32 v214, v133, v132 offset0:104 offset1:105
	v_mul_f32_e32 v132, v90, v130
	v_mul_f32_e32 v134, v91, v130
	v_mul_f32_e32 v133, v26, v131
	ds_write2st64_b32 v214, v132, v134 offset0:42 offset1:43
	v_mul_f32_e32 v132, v27, v131
	ds_write2st64_b32 v214, v133, v132 offset0:106 offset1:107
	v_mul_f32_e32 v132, v92, v130
	v_mul_f32_e32 v134, v93, v130
	v_mul_f32_e32 v133, v28, v131
	ds_write2st64_b32 v214, v132, v134 offset0:44 offset1:45
	v_mul_f32_e32 v132, v29, v131
	ds_write2st64_b32 v214, v133, v132 offset0:108 offset1:109
	v_mul_f32_e32 v132, v94, v130
	v_mul_f32_e32 v134, v95, v130
	v_mul_f32_e32 v133, v30, v131
	ds_write2st64_b32 v214, v132, v134 offset0:46 offset1:47
	v_mul_f32_e32 v132, v31, v131
	ds_write2st64_b32 v214, v133, v132 offset0:110 offset1:111
	v_mul_f32_e32 v132, v64, v130
	v_mul_f32_e32 v134, v65, v130
	v_mul_f32_e32 v133, v0, v131
	ds_write2st64_b32 v214, v132, v134 offset0:48 offset1:49
	v_mul_f32_e32 v132, v1, v131
	ds_write2st64_b32 v214, v133, v132 offset0:112 offset1:113
	v_mul_f32_e32 v132, v66, v130
	v_mul_f32_e32 v134, v67, v130
	v_mul_f32_e32 v133, v2, v131
	ds_write2st64_b32 v214, v132, v134 offset0:50 offset1:51
	v_mul_f32_e32 v132, v3, v131
	ds_write2st64_b32 v214, v133, v132 offset0:114 offset1:115
	v_mul_f32_e32 v132, v68, v130
	v_mul_f32_e32 v134, v69, v130
	v_mul_f32_e32 v133, v4, v131
	ds_write2st64_b32 v214, v132, v134 offset0:52 offset1:53
	v_mul_f32_e32 v132, v5, v131
	ds_write2st64_b32 v214, v133, v132 offset0:116 offset1:117
	v_mul_f32_e32 v132, v70, v130
	v_mul_f32_e32 v134, v71, v130
	v_mul_f32_e32 v133, v6, v131
	ds_write2st64_b32 v214, v132, v134 offset0:54 offset1:55
	v_mul_f32_e32 v132, v7, v131
	ds_write2st64_b32 v214, v133, v132 offset0:118 offset1:119
	v_mul_f32_e32 v132, v72, v130
	v_mul_f32_e32 v134, v73, v130
	v_mul_f32_e32 v133, v8, v131
	ds_write2st64_b32 v214, v132, v134 offset0:56 offset1:57
	v_mul_f32_e32 v132, v9, v131
	ds_write2st64_b32 v214, v133, v132 offset0:120 offset1:121
	v_mul_f32_e32 v132, v74, v130
	v_mul_f32_e32 v134, v75, v130
	v_mul_f32_e32 v133, v10, v131
	ds_write2st64_b32 v214, v132, v134 offset0:58 offset1:59
	v_mul_f32_e32 v132, v11, v131
	ds_write2st64_b32 v214, v133, v132 offset0:122 offset1:123
	v_mul_f32_e32 v132, v76, v130
	v_mul_f32_e32 v134, v77, v130
	v_mul_f32_e32 v133, v12, v131
	ds_write2st64_b32 v214, v132, v134 offset0:60 offset1:61
	v_mul_f32_e32 v132, v13, v131
	ds_write2st64_b32 v214, v133, v132 offset0:124 offset1:125
	v_mul_f32_e32 v132, v78, v130
	v_mul_f32_e32 v130, v79, v130
	v_mul_f32_e32 v133, v14, v131
	ds_write2st64_b32 v214, v132, v130 offset0:62 offset1:63
	v_mul_f32_e32 v130, v15, v131
	ds_write2st64_b32 v214, v133, v130 offset0:126 offset1:127
